# grid barrier: first arriver of each XCD starts an early L2 write-back so the last arriver's release has less to flush
# speedup vs baseline: 1.0080x; 1.0080x over previous
.LBB0_1934:
	s_or_b64 exec, exec, s[2:3]
	v_cvt_f32_u32_e32 v5, v3
	s_waitcnt vmcnt(0)
	v_readfirstlane_b32 s2, v4
	v_sub_u32_e32 v4, 0, v3
	v_rcp_iflag_f32_e32 v5, v5
	v_add_u32_e32 v6, s2, v0
	v_mul_f32_e32 v5, 0x4f7ffffe, v5
	v_cvt_u32_f32_e32 v5, v5
	v_mul_lo_u32 v0, v4, v5
	v_mul_hi_u32 v0, v5, v0
	v_add_u32_e32 v0, v5, v0
	v_mul_hi_u32 v0, v6, v0
	v_mul_lo_u32 v4, v0, v3
	v_sub_u32_e32 v4, v6, v4
	v_add_u32_e32 v5, 1, v0
	v_cmp_ge_u32_e32 vcc, v4, v3
	s_nop 1
	v_cndmask_b32_e32 v0, v0, v5, vcc
	v_sub_u32_e32 v5, v4, v3
	v_cndmask_b32_e32 v4, v4, v5, vcc
	v_add_u32_e32 v5, 1, v0
	v_cmp_ge_u32_e32 vcc, v4, v3
	v_add_u32_e32 v4, 1, v6
	s_nop 0
	v_cndmask_b32_e32 v0, v0, v5, vcc
	v_mul_lo_u32 v5, v3, v0
	v_cmp_eq_u32_e32 vcc, v6, v5
	s_cbranch_vccz .Lef_skip
	buffer_wbl2 sc1
.Lef_skip:
	v_add_u32_e32 v3, v5, v3
	v_cmp_ne_u32_e32 vcc, v4, v3
	s_and_saveexec_b64 s[2:3], vcc
	s_xor_b64 s[2:3], exec, s[2:3]
	s_cbranch_execz .LBB0_1948
	v_readlane_b32 s4, v254, 29
	v_readlane_b32 s5, v254, 30
	s_waitcnt lgkmcnt(0)
	s_nop 3
	global_load_dword v2, v1, s[4:5] sc1
	s_waitcnt vmcnt(0)
	v_cmp_eq_u32_e32 vcc, v2, v0
	s_and_saveexec_b64 s[4:5], vcc
	s_cbranch_execz .LBB0_1947
	s_mov_b32 s17, 1
	s_mov_b64 s[6:7], 0
	s_branch .LBB0_1938
